# grid barrier after a non-final layer LN2 phase dropped
# speedup vs baseline: 1.0046x; 1.0017x over previous
; #define SEAM(k) do { if (IN(k) && IN((k) + 1)) xcd_barrier(bar); } while (0)
; __global__ void __launch_bounds__(NTHREADS, 2) mk_fwd(Args args) {
;     ...
;         if (IN(pb + 14)) { phase_peer_ln2(l, nrows, last, wv);
;     ...
;             if (last) { phase_peer_ln2(l, nrows, last, wv); phase_peer_ln2(l, nrows, last, wv); }
;     ...
;         }
;         SEAM(pb + 14);
.LBB0_1154:
	v_readlane_b32 s0, v254, 30
	s_add_i32 s0, s0, 15
	s_cmp_ge_i32 s0, s83
	s_getpc_b64 s[98:99]
